# SWA-branch queries: RoPE applied in registers when the attention unit loads Q (same f32 math, bf16 result) instead of a separate in-place pass; rope phase now rotates only the NSA queries and the keys
# speedup vs baseline: 1.0024x; 1.0024x over previous
.LBB0_333:
	v_lshrrev_b32_e32 v58, 7, v26
	v_lshlrev_b32_e32 v58, 12, v58
	v_and_b32_e32 v59, 2, v26
	v_lshlrev_b32_e32 v59, 9, v59
	v_or_b32_e32 v58, v58, v59
	v_and_b32_e32 v59, 1, v26
	v_lshlrev_b32_e32 v59, 4, v59
	v_or_b32_e32 v58, v58, v59
	v_bfe_u32 v59, v26, 2, 5
	v_lshlrev_b32_e32 v59, 5, v59
	v_or_b32_e32 v58, v58, v59
	v_add_co_u32_e32 v60, vcc, v56, v58
	s_nop 1
	v_addc_co_u32_e32 v61, vcc, 0, v57, vcc
	v_ashrrev_i32_e32 v22, 2, v26
	v_ashrrev_i32_e32 v23, 31, v22
	v_lshlrev_b32_e32 v0, 3, v26
	v_and_b32_e32 v24, 24, v0
	v_lshlrev_b64 v[2:3], 8, v[22:23]
	v_lshl_add_u64 v[2:3], v[20:21], 0, v[2:3]
	v_lshlrev_b32_e32 v0, 3, v24
	v_lshl_add_u64 v[14:15], v[2:3], 0, v[0:1]
	global_load_dwordx4 v[2:5], v[14:15], off
	global_load_dwordx4 v[6:9], v[14:15], off offset:16
	global_load_dwordx4 v[10:13], v[14:15], off offset:32
	s_nop 0
	global_load_dwordx4 v[14:17], v[14:15], off offset:48
	v_mad_i64_i32 v[22:23], s[8:9], v22, s61, v[18:19]
	v_lshlrev_b32_e32 v0, 1, v24
	v_lshl_add_u64 v[22:23], v[22:23], 0, v[0:1]
	s_mov_b32 s10, 0
	s_movk_i32 s11, 0x200
	s_movk_i32 s12, 0x100
	s_waitcnt vmcnt(0) lgkmcnt(0)
	v_mov_b32_e32 v24, v15
	v_mov_b32_e32 v25, v17
	v_mov_b32_e32 v15, v16
	v_mov_b32_e32 v16, v11
	v_mov_b32_e32 v17, v13
	v_mov_b32_e32 v11, v12
	v_mov_b32_e32 v12, v7
	v_mov_b32_e32 v13, v9
	v_mov_b32_e32 v7, v8
	v_mov_b32_e32 v8, v3
	v_mov_b32_e32 v9, v5
	v_mov_b32_e32 v3, v4
	s_movk_i32 s74, 0x0
	v_lshl_add_u64 v[4:5], s[74:75], 1, v[22:23]
	global_load_dwordx4 v[28:31], v[4:5], off
	global_load_dwordx4 v[32:35], v[4:5], off offset:64
	s_waitcnt vmcnt(0) lgkmcnt(0)
	v_lshlrev_b32_e32 v36, 16, v28
	v_lshlrev_b32_e32 v38, 16, v32
	v_and_b32_e32 v39, 0xffff0000, v32
	v_and_b32_e32 v37, 0xffff0000, v28
	v_pk_mul_f32 v[40:41], v[2:3], v[38:39]
	v_pk_mul_f32 v[38:39], v[8:9], v[38:39]
	v_lshlrev_b32_e32 v32, 16, v33
	v_and_b32_e32 v33, 0xffff0000, v33
	v_pk_fma_f32 v[40:41], v[8:9], v[36:37], v[40:41]
	v_pk_fma_f32 v[36:37], v[2:3], v[36:37], v[38:39] neg_lo:[0,0,1] neg_hi:[0,0,1]
	v_lshlrev_b32_e32 v28, 16, v29
	v_and_b32_e32 v29, 0xffff0000, v29
	v_pk_mul_f32 v[38:39], v[6:7], v[32:33]
	v_pk_mul_f32 v[32:33], v[12:13], v[32:33]
	v_lshlrev_b32_e32 v42, 16, v34
	v_and_b32_e32 v43, 0xffff0000, v34
	v_pk_fma_f32 v[38:39], v[12:13], v[28:29], v[38:39]
	v_pk_fma_f32 v[32:33], v[6:7], v[28:29], v[32:33] neg_lo:[0,0,1] neg_hi:[0,0,1]
	v_lshlrev_b32_e32 v28, 16, v30
	v_and_b32_e32 v29, 0xffff0000, v30
	v_pk_mul_f32 v[44:45], v[10:11], v[42:43]
	v_pk_mul_f32 v[42:43], v[16:17], v[42:43]
	v_pk_fma_f32 v[44:45], v[16:17], v[28:29], v[44:45]
	v_pk_fma_f32 v[42:43], v[10:11], v[28:29], v[42:43] neg_lo:[0,0,1] neg_hi:[0,0,1]
	v_lshlrev_b32_e32 v28, 16, v31
	v_and_b32_e32 v29, 0xffff0000, v31
	v_lshlrev_b32_e32 v30, 16, v35
	v_and_b32_e32 v31, 0xffff0000, v35
	v_pk_mul_f32 v[34:35], v[14:15], v[30:31]
	v_pk_mul_f32 v[30:31], v[24:25], v[30:31]
	v_pk_fma_f32 v[34:35], v[24:25], v[28:29], v[34:35]
	v_pk_fma_f32 v[46:47], v[14:15], v[28:29], v[30:31] neg_lo:[0,0,1] neg_hi:[0,0,1]
	v_cvt_pk_bf16_f32 v28, v36, v37
	v_cvt_pk_bf16_f32 v29, v32, v33
	v_cvt_pk_bf16_f32 v30, v42, v43
	v_cvt_pk_bf16_f32 v31, v46, v47
	global_store_dwordx4 v[4:5], v[28:31], off
	s_nop 1
	v_cvt_pk_bf16_f32 v28, v40, v41
	v_cvt_pk_bf16_f32 v29, v38, v39
	v_cvt_pk_bf16_f32 v30, v44, v45
	v_cvt_pk_bf16_f32 v31, v34, v35
	global_store_dwordx4 v[4:5], v[28:31], off offset:64
	s_movk_i32 s74, 0x40
	v_lshl_add_u64 v[4:5], s[74:75], 1, v[22:23]
	global_load_dwordx4 v[28:31], v[4:5], off
	global_load_dwordx4 v[32:35], v[4:5], off offset:64
	s_waitcnt vmcnt(0) lgkmcnt(0)
	v_lshlrev_b32_e32 v36, 16, v28
	v_lshlrev_b32_e32 v38, 16, v32
	v_and_b32_e32 v39, 0xffff0000, v32
	v_and_b32_e32 v37, 0xffff0000, v28
	v_pk_mul_f32 v[40:41], v[2:3], v[38:39]
	v_pk_mul_f32 v[38:39], v[8:9], v[38:39]
	v_lshlrev_b32_e32 v32, 16, v33
	v_and_b32_e32 v33, 0xffff0000, v33
	v_pk_fma_f32 v[40:41], v[8:9], v[36:37], v[40:41]
	v_pk_fma_f32 v[36:37], v[2:3], v[36:37], v[38:39] neg_lo:[0,0,1] neg_hi:[0,0,1]
	v_lshlrev_b32_e32 v28, 16, v29
	v_and_b32_e32 v29, 0xffff0000, v29
	v_pk_mul_f32 v[38:39], v[6:7], v[32:33]
	v_pk_mul_f32 v[32:33], v[12:13], v[32:33]
	v_lshlrev_b32_e32 v42, 16, v34
	v_and_b32_e32 v43, 0xffff0000, v34
	v_pk_fma_f32 v[38:39], v[12:13], v[28:29], v[38:39]
	v_pk_fma_f32 v[32:33], v[6:7], v[28:29], v[32:33] neg_lo:[0,0,1] neg_hi:[0,0,1]
	v_lshlrev_b32_e32 v28, 16, v30
	v_and_b32_e32 v29, 0xffff0000, v30
	v_pk_mul_f32 v[44:45], v[10:11], v[42:43]
	v_pk_mul_f32 v[42:43], v[16:17], v[42:43]
	v_pk_fma_f32 v[44:45], v[16:17], v[28:29], v[44:45]
	v_pk_fma_f32 v[42:43], v[10:11], v[28:29], v[42:43] neg_lo:[0,0,1] neg_hi:[0,0,1]
	v_lshlrev_b32_e32 v28, 16, v31
	v_and_b32_e32 v29, 0xffff0000, v31
	v_lshlrev_b32_e32 v30, 16, v35
	v_and_b32_e32 v31, 0xffff0000, v35
	v_pk_mul_f32 v[34:35], v[14:15], v[30:31]
	v_pk_mul_f32 v[30:31], v[24:25], v[30:31]
	v_pk_fma_f32 v[34:35], v[24:25], v[28:29], v[34:35]
	v_pk_fma_f32 v[46:47], v[14:15], v[28:29], v[30:31] neg_lo:[0,0,1] neg_hi:[0,0,1]
	v_cvt_pk_bf16_f32 v28, v36, v37
	v_cvt_pk_bf16_f32 v29, v32, v33
	v_cvt_pk_bf16_f32 v30, v42, v43
	v_cvt_pk_bf16_f32 v31, v46, v47
	global_store_dwordx4 v[4:5], v[28:31], off
	s_nop 1
	v_cvt_pk_bf16_f32 v28, v40, v41
	v_cvt_pk_bf16_f32 v29, v38, v39
	v_cvt_pk_bf16_f32 v30, v44, v45
	v_cvt_pk_bf16_f32 v31, v34, v35
	global_store_dwordx4 v[4:5], v[28:31], off offset:64
	s_movk_i32 s74, 0x80
	v_lshl_add_u64 v[4:5], s[74:75], 1, v[22:23]
	global_load_dwordx4 v[28:31], v[4:5], off
	global_load_dwordx4 v[32:35], v[4:5], off offset:64
	s_waitcnt vmcnt(0) lgkmcnt(0)
	v_lshlrev_b32_e32 v36, 16, v28
	v_lshlrev_b32_e32 v38, 16, v32
	v_and_b32_e32 v39, 0xffff0000, v32
	v_and_b32_e32 v37, 0xffff0000, v28
	v_pk_mul_f32 v[40:41], v[2:3], v[38:39]
	v_pk_mul_f32 v[38:39], v[8:9], v[38:39]
	v_lshlrev_b32_e32 v32, 16, v33
	v_and_b32_e32 v33, 0xffff0000, v33
	v_pk_fma_f32 v[40:41], v[8:9], v[36:37], v[40:41]
	v_pk_fma_f32 v[36:37], v[2:3], v[36:37], v[38:39] neg_lo:[0,0,1] neg_hi:[0,0,1]
	v_lshlrev_b32_e32 v28, 16, v29
	v_and_b32_e32 v29, 0xffff0000, v29
	v_pk_mul_f32 v[38:39], v[6:7], v[32:33]
	v_pk_mul_f32 v[32:33], v[12:13], v[32:33]
	v_lshlrev_b32_e32 v42, 16, v34
	v_and_b32_e32 v43, 0xffff0000, v34
	v_pk_fma_f32 v[38:39], v[12:13], v[28:29], v[38:39]
	v_pk_fma_f32 v[32:33], v[6:7], v[28:29], v[32:33] neg_lo:[0,0,1] neg_hi:[0,0,1]
	v_lshlrev_b32_e32 v28, 16, v30
	v_and_b32_e32 v29, 0xffff0000, v30
	v_pk_mul_f32 v[44:45], v[10:11], v[42:43]
	v_pk_mul_f32 v[42:43], v[16:17], v[42:43]
	v_pk_fma_f32 v[44:45], v[16:17], v[28:29], v[44:45]
	v_pk_fma_f32 v[42:43], v[10:11], v[28:29], v[42:43] neg_lo:[0,0,1] neg_hi:[0,0,1]
	v_lshlrev_b32_e32 v28, 16, v31
	v_and_b32_e32 v29, 0xffff0000, v31
	v_lshlrev_b32_e32 v30, 16, v35
	v_and_b32_e32 v31, 0xffff0000, v35
	v_pk_mul_f32 v[34:35], v[14:15], v[30:31]
	v_pk_mul_f32 v[30:31], v[24:25], v[30:31]
	v_pk_fma_f32 v[34:35], v[24:25], v[28:29], v[34:35]
	v_pk_fma_f32 v[46:47], v[14:15], v[28:29], v[30:31] neg_lo:[0,0,1] neg_hi:[0,0,1]
	v_cvt_pk_bf16_f32 v28, v36, v37
	v_cvt_pk_bf16_f32 v29, v32, v33
	v_cvt_pk_bf16_f32 v30, v42, v43
	v_cvt_pk_bf16_f32 v31, v46, v47
	global_store_dwordx4 v[4:5], v[28:31], off
	s_nop 1
	v_cvt_pk_bf16_f32 v28, v40, v41
	v_cvt_pk_bf16_f32 v29, v38, v39
	v_cvt_pk_bf16_f32 v30, v44, v45
	v_cvt_pk_bf16_f32 v31, v34, v35
	global_store_dwordx4 v[4:5], v[28:31], off offset:64
	s_movk_i32 s74, 0xc0
	v_lshl_add_u64 v[4:5], s[74:75], 1, v[22:23]
	global_load_dwordx4 v[28:31], v[4:5], off
	global_load_dwordx4 v[32:35], v[4:5], off offset:64
	s_waitcnt vmcnt(0) lgkmcnt(0)
	v_lshlrev_b32_e32 v36, 16, v28
	v_lshlrev_b32_e32 v38, 16, v32
	v_and_b32_e32 v39, 0xffff0000, v32
	v_and_b32_e32 v37, 0xffff0000, v28
	v_pk_mul_f32 v[40:41], v[2:3], v[38:39]
	v_pk_mul_f32 v[38:39], v[8:9], v[38:39]
	v_lshlrev_b32_e32 v32, 16, v33
	v_and_b32_e32 v33, 0xffff0000, v33
	v_pk_fma_f32 v[40:41], v[8:9], v[36:37], v[40:41]
	v_pk_fma_f32 v[36:37], v[2:3], v[36:37], v[38:39] neg_lo:[0,0,1] neg_hi:[0,0,1]
	v_lshlrev_b32_e32 v28, 16, v29
	v_and_b32_e32 v29, 0xffff0000, v29
	v_pk_mul_f32 v[38:39], v[6:7], v[32:33]
	v_pk_mul_f32 v[32:33], v[12:13], v[32:33]
	v_lshlrev_b32_e32 v42, 16, v34
	v_and_b32_e32 v43, 0xffff0000, v34
	v_pk_fma_f32 v[38:39], v[12:13], v[28:29], v[38:39]
	v_pk_fma_f32 v[32:33], v[6:7], v[28:29], v[32:33] neg_lo:[0,0,1] neg_hi:[0,0,1]
	v_lshlrev_b32_e32 v28, 16, v30
	v_and_b32_e32 v29, 0xffff0000, v30
	v_pk_mul_f32 v[44:45], v[10:11], v[42:43]
	v_pk_mul_f32 v[42:43], v[16:17], v[42:43]
	v_pk_fma_f32 v[44:45], v[16:17], v[28:29], v[44:45]
	v_pk_fma_f32 v[42:43], v[10:11], v[28:29], v[42:43] neg_lo:[0,0,1] neg_hi:[0,0,1]
	v_lshlrev_b32_e32 v28, 16, v31
	v_and_b32_e32 v29, 0xffff0000, v31
	v_lshlrev_b32_e32 v30, 16, v35
	v_and_b32_e32 v31, 0xffff0000, v35
	v_pk_mul_f32 v[34:35], v[14:15], v[30:31]
	v_pk_mul_f32 v[30:31], v[24:25], v[30:31]
	v_pk_fma_f32 v[34:35], v[24:25], v[28:29], v[34:35]
	v_pk_fma_f32 v[46:47], v[14:15], v[28:29], v[30:31] neg_lo:[0,0,1] neg_hi:[0,0,1]
	v_cvt_pk_bf16_f32 v28, v36, v37
	v_cvt_pk_bf16_f32 v29, v32, v33
	v_cvt_pk_bf16_f32 v30, v42, v43
	v_cvt_pk_bf16_f32 v31, v46, v47
	global_store_dwordx4 v[4:5], v[28:31], off
	s_nop 1
	v_cvt_pk_bf16_f32 v28, v40, v41
	v_cvt_pk_bf16_f32 v29, v38, v39
	v_cvt_pk_bf16_f32 v30, v44, v45
	v_cvt_pk_bf16_f32 v31, v34, v35
	global_store_dwordx4 v[4:5], v[28:31], off offset:64
	s_movk_i32 s74, 0x100
	v_lshl_add_u64 v[4:5], s[74:75], 1, v[22:23]
	global_load_dwordx4 v[28:31], v[4:5], off
	global_load_dwordx4 v[32:35], v[4:5], off offset:64
	s_waitcnt vmcnt(0) lgkmcnt(0)
	v_lshlrev_b32_e32 v36, 16, v28
	v_lshlrev_b32_e32 v38, 16, v32
	v_and_b32_e32 v39, 0xffff0000, v32
	v_and_b32_e32 v37, 0xffff0000, v28
	v_pk_mul_f32 v[40:41], v[2:3], v[38:39]
	v_pk_mul_f32 v[38:39], v[8:9], v[38:39]
	v_lshlrev_b32_e32 v32, 16, v33
	v_and_b32_e32 v33, 0xffff0000, v33
	v_pk_fma_f32 v[40:41], v[8:9], v[36:37], v[40:41]
	v_pk_fma_f32 v[36:37], v[2:3], v[36:37], v[38:39] neg_lo:[0,0,1] neg_hi:[0,0,1]
	v_lshlrev_b32_e32 v28, 16, v29
	v_and_b32_e32 v29, 0xffff0000, v29
	v_pk_mul_f32 v[38:39], v[6:7], v[32:33]
	v_pk_mul_f32 v[32:33], v[12:13], v[32:33]
	v_lshlrev_b32_e32 v42, 16, v34
	v_and_b32_e32 v43, 0xffff0000, v34
	v_pk_fma_f32 v[38:39], v[12:13], v[28:29], v[38:39]
	v_pk_fma_f32 v[32:33], v[6:7], v[28:29], v[32:33] neg_lo:[0,0,1] neg_hi:[0,0,1]
	v_lshlrev_b32_e32 v28, 16, v30
	v_and_b32_e32 v29, 0xffff0000, v30
	v_pk_mul_f32 v[44:45], v[10:11], v[42:43]
	v_pk_mul_f32 v[42:43], v[16:17], v[42:43]
	v_pk_fma_f32 v[44:45], v[16:17], v[28:29], v[44:45]
	v_pk_fma_f32 v[42:43], v[10:11], v[28:29], v[42:43] neg_lo:[0,0,1] neg_hi:[0,0,1]
	v_lshlrev_b32_e32 v28, 16, v31
	v_and_b32_e32 v29, 0xffff0000, v31
	v_lshlrev_b32_e32 v30, 16, v35
	v_and_b32_e32 v31, 0xffff0000, v35
	v_pk_mul_f32 v[34:35], v[14:15], v[30:31]
	v_pk_mul_f32 v[30:31], v[24:25], v[30:31]
	v_pk_fma_f32 v[34:35], v[24:25], v[28:29], v[34:35]
	v_pk_fma_f32 v[46:47], v[14:15], v[28:29], v[30:31] neg_lo:[0,0,1] neg_hi:[0,0,1]
	v_cvt_pk_bf16_f32 v28, v36, v37
	v_cvt_pk_bf16_f32 v29, v32, v33
	v_cvt_pk_bf16_f32 v30, v42, v43
	v_cvt_pk_bf16_f32 v31, v46, v47
	global_store_dwordx4 v[4:5], v[28:31], off
	s_nop 1
	v_cvt_pk_bf16_f32 v28, v40, v41
	v_cvt_pk_bf16_f32 v29, v38, v39
	v_cvt_pk_bf16_f32 v30, v44, v45
	v_cvt_pk_bf16_f32 v31, v34, v35
	global_store_dwordx4 v[4:5], v[28:31], off offset:64
	s_movk_i32 s74, 0x140
	v_lshl_add_u64 v[4:5], s[74:75], 1, v[22:23]
	global_load_dwordx4 v[28:31], v[4:5], off
	global_load_dwordx4 v[32:35], v[4:5], off offset:64
	s_waitcnt vmcnt(0) lgkmcnt(0)
	v_lshlrev_b32_e32 v36, 16, v28
	v_lshlrev_b32_e32 v38, 16, v32
	v_and_b32_e32 v39, 0xffff0000, v32
	v_and_b32_e32 v37, 0xffff0000, v28
	v_pk_mul_f32 v[40:41], v[2:3], v[38:39]
	v_pk_mul_f32 v[38:39], v[8:9], v[38:39]
	v_lshlrev_b32_e32 v32, 16, v33
	v_and_b32_e32 v33, 0xffff0000, v33
	v_pk_fma_f32 v[40:41], v[8:9], v[36:37], v[40:41]
	v_pk_fma_f32 v[36:37], v[2:3], v[36:37], v[38:39] neg_lo:[0,0,1] neg_hi:[0,0,1]
	v_lshlrev_b32_e32 v28, 16, v29
	v_and_b32_e32 v29, 0xffff0000, v29
	v_pk_mul_f32 v[38:39], v[6:7], v[32:33]
	v_pk_mul_f32 v[32:33], v[12:13], v[32:33]
	v_lshlrev_b32_e32 v42, 16, v34
	v_and_b32_e32 v43, 0xffff0000, v34
	v_pk_fma_f32 v[38:39], v[12:13], v[28:29], v[38:39]
	v_pk_fma_f32 v[32:33], v[6:7], v[28:29], v[32:33] neg_lo:[0,0,1] neg_hi:[0,0,1]
	v_lshlrev_b32_e32 v28, 16, v30
	v_and_b32_e32 v29, 0xffff0000, v30
	v_pk_mul_f32 v[44:45], v[10:11], v[42:43]
	v_pk_mul_f32 v[42:43], v[16:17], v[42:43]
	v_pk_fma_f32 v[44:45], v[16:17], v[28:29], v[44:45]
	v_pk_fma_f32 v[42:43], v[10:11], v[28:29], v[42:43] neg_lo:[0,0,1] neg_hi:[0,0,1]
	v_lshlrev_b32_e32 v28, 16, v31
	v_and_b32_e32 v29, 0xffff0000, v31
	v_lshlrev_b32_e32 v30, 16, v35
	v_and_b32_e32 v31, 0xffff0000, v35
	v_pk_mul_f32 v[34:35], v[14:15], v[30:31]
	v_pk_mul_f32 v[30:31], v[24:25], v[30:31]
	v_pk_fma_f32 v[34:35], v[24:25], v[28:29], v[34:35]
	v_pk_fma_f32 v[46:47], v[14:15], v[28:29], v[30:31] neg_lo:[0,0,1] neg_hi:[0,0,1]
	v_cvt_pk_bf16_f32 v28, v36, v37
	v_cvt_pk_bf16_f32 v29, v32, v33
	v_cvt_pk_bf16_f32 v30, v42, v43
	v_cvt_pk_bf16_f32 v31, v46, v47
	global_store_dwordx4 v[4:5], v[28:31], off
	s_nop 1
	v_cvt_pk_bf16_f32 v28, v40, v41
	v_cvt_pk_bf16_f32 v29, v38, v39
	v_cvt_pk_bf16_f32 v30, v44, v45
	v_cvt_pk_bf16_f32 v31, v34, v35
	global_store_dwordx4 v[4:5], v[28:31], off offset:64
	s_movk_i32 s74, 0x180
	v_lshl_add_u64 v[4:5], s[74:75], 1, v[22:23]
	global_load_dwordx4 v[28:31], v[4:5], off
	global_load_dwordx4 v[32:35], v[4:5], off offset:64
	s_waitcnt vmcnt(0) lgkmcnt(0)
	v_lshlrev_b32_e32 v36, 16, v28
	v_lshlrev_b32_e32 v38, 16, v32
	v_and_b32_e32 v39, 0xffff0000, v32
	v_and_b32_e32 v37, 0xffff0000, v28
	v_pk_mul_f32 v[40:41], v[2:3], v[38:39]
	v_pk_mul_f32 v[38:39], v[8:9], v[38:39]
	v_lshlrev_b32_e32 v32, 16, v33
	v_and_b32_e32 v33, 0xffff0000, v33
	v_pk_fma_f32 v[40:41], v[8:9], v[36:37], v[40:41]
	v_pk_fma_f32 v[36:37], v[2:3], v[36:37], v[38:39] neg_lo:[0,0,1] neg_hi:[0,0,1]
	v_lshlrev_b32_e32 v28, 16, v29
	v_and_b32_e32 v29, 0xffff0000, v29
	v_pk_mul_f32 v[38:39], v[6:7], v[32:33]
	v_pk_mul_f32 v[32:33], v[12:13], v[32:33]
	v_lshlrev_b32_e32 v42, 16, v34
	v_and_b32_e32 v43, 0xffff0000, v34
	v_pk_fma_f32 v[38:39], v[12:13], v[28:29], v[38:39]
	v_pk_fma_f32 v[32:33], v[6:7], v[28:29], v[32:33] neg_lo:[0,0,1] neg_hi:[0,0,1]
	v_lshlrev_b32_e32 v28, 16, v30
	v_and_b32_e32 v29, 0xffff0000, v30
	v_pk_mul_f32 v[44:45], v[10:11], v[42:43]
	v_pk_mul_f32 v[42:43], v[16:17], v[42:43]
	v_pk_fma_f32 v[44:45], v[16:17], v[28:29], v[44:45]
	v_pk_fma_f32 v[42:43], v[10:11], v[28:29], v[42:43] neg_lo:[0,0,1] neg_hi:[0,0,1]
	v_lshlrev_b32_e32 v28, 16, v31
	v_and_b32_e32 v29, 0xffff0000, v31
	v_lshlrev_b32_e32 v30, 16, v35
	v_and_b32_e32 v31, 0xffff0000, v35
	v_pk_mul_f32 v[34:35], v[14:15], v[30:31]
	v_pk_mul_f32 v[30:31], v[24:25], v[30:31]
	v_pk_fma_f32 v[34:35], v[24:25], v[28:29], v[34:35]
	v_pk_fma_f32 v[46:47], v[14:15], v[28:29], v[30:31] neg_lo:[0,0,1] neg_hi:[0,0,1]
	v_cvt_pk_bf16_f32 v28, v36, v37
	v_cvt_pk_bf16_f32 v29, v32, v33
	v_cvt_pk_bf16_f32 v30, v42, v43
	v_cvt_pk_bf16_f32 v31, v46, v47
	global_store_dwordx4 v[4:5], v[28:31], off
	s_nop 1
	v_cvt_pk_bf16_f32 v28, v40, v41
	v_cvt_pk_bf16_f32 v29, v38, v39
	v_cvt_pk_bf16_f32 v30, v44, v45
	v_cvt_pk_bf16_f32 v31, v34, v35
	global_store_dwordx4 v[4:5], v[28:31], off offset:64
	s_movk_i32 s74, 0x1c0
	v_lshl_add_u64 v[4:5], s[74:75], 1, v[22:23]
	global_load_dwordx4 v[28:31], v[4:5], off
	global_load_dwordx4 v[32:35], v[4:5], off offset:64
	s_waitcnt vmcnt(0) lgkmcnt(0)
	v_lshlrev_b32_e32 v36, 16, v28
	v_lshlrev_b32_e32 v38, 16, v32
	v_and_b32_e32 v39, 0xffff0000, v32
	v_and_b32_e32 v37, 0xffff0000, v28
	v_pk_mul_f32 v[40:41], v[2:3], v[38:39]
	v_pk_mul_f32 v[38:39], v[8:9], v[38:39]
	v_lshlrev_b32_e32 v32, 16, v33
	v_and_b32_e32 v33, 0xffff0000, v33
	v_pk_fma_f32 v[40:41], v[8:9], v[36:37], v[40:41]
	v_pk_fma_f32 v[36:37], v[2:3], v[36:37], v[38:39] neg_lo:[0,0,1] neg_hi:[0,0,1]
	v_lshlrev_b32_e32 v28, 16, v29
	v_and_b32_e32 v29, 0xffff0000, v29
	v_pk_mul_f32 v[38:39], v[6:7], v[32:33]
	v_pk_mul_f32 v[32:33], v[12:13], v[32:33]
	v_lshlrev_b32_e32 v42, 16, v34
	v_and_b32_e32 v43, 0xffff0000, v34
	v_pk_fma_f32 v[38:39], v[12:13], v[28:29], v[38:39]
	v_pk_fma_f32 v[32:33], v[6:7], v[28:29], v[32:33] neg_lo:[0,0,1] neg_hi:[0,0,1]
	v_lshlrev_b32_e32 v28, 16, v30
	v_and_b32_e32 v29, 0xffff0000, v30
	v_pk_mul_f32 v[44:45], v[10:11], v[42:43]
	v_pk_mul_f32 v[42:43], v[16:17], v[42:43]
	v_pk_fma_f32 v[44:45], v[16:17], v[28:29], v[44:45]
	v_pk_fma_f32 v[42:43], v[10:11], v[28:29], v[42:43] neg_lo:[0,0,1] neg_hi:[0,0,1]
	v_lshlrev_b32_e32 v28, 16, v31
	v_and_b32_e32 v29, 0xffff0000, v31
	v_lshlrev_b32_e32 v30, 16, v35
	v_and_b32_e32 v31, 0xffff0000, v35
	v_pk_mul_f32 v[34:35], v[14:15], v[30:31]
	v_pk_mul_f32 v[30:31], v[24:25], v[30:31]
	v_pk_fma_f32 v[34:35], v[24:25], v[28:29], v[34:35]
	v_pk_fma_f32 v[46:47], v[14:15], v[28:29], v[30:31] neg_lo:[0,0,1] neg_hi:[0,0,1]
	v_cvt_pk_bf16_f32 v28, v36, v37
	v_cvt_pk_bf16_f32 v29, v32, v33
	v_cvt_pk_bf16_f32 v30, v42, v43
	v_cvt_pk_bf16_f32 v31, v46, v47
	global_store_dwordx4 v[4:5], v[28:31], off
	s_nop 1
	v_cvt_pk_bf16_f32 v28, v40, v41
	v_cvt_pk_bf16_f32 v29, v38, v39
	v_cvt_pk_bf16_f32 v30, v44, v45
	v_cvt_pk_bf16_f32 v31, v34, v35
	global_store_dwordx4 v[4:5], v[28:31], off offset:64
	s_movk_i32 s74, 0x300
	v_lshl_add_u64 v[4:5], s[74:75], 1, v[22:23]
	s_and_b32 s98, s74, 64
	s_lshl_b32 s98, s98, 16
	v_lshl_add_u64 v[62:63], v[60:61], 0, s[98:99]
	global_load_dwordx4 v[28:31], v[4:5], off
	global_load_dwordx4 v[32:35], v[4:5], off offset:64
	s_waitcnt vmcnt(0) lgkmcnt(0)
	v_lshlrev_b32_e32 v36, 16, v28
	v_lshlrev_b32_e32 v38, 16, v32
	v_and_b32_e32 v39, 0xffff0000, v32
	v_and_b32_e32 v37, 0xffff0000, v28
	v_pk_mul_f32 v[40:41], v[2:3], v[38:39]
	v_pk_mul_f32 v[38:39], v[8:9], v[38:39]
	v_lshlrev_b32_e32 v32, 16, v33
	v_and_b32_e32 v33, 0xffff0000, v33
	v_pk_fma_f32 v[40:41], v[8:9], v[36:37], v[40:41]
	v_pk_fma_f32 v[36:37], v[2:3], v[36:37], v[38:39] neg_lo:[0,0,1] neg_hi:[0,0,1]
	v_lshlrev_b32_e32 v28, 16, v29
	v_and_b32_e32 v29, 0xffff0000, v29
	v_pk_mul_f32 v[38:39], v[6:7], v[32:33]
	v_pk_mul_f32 v[32:33], v[12:13], v[32:33]
	v_lshlrev_b32_e32 v42, 16, v34
	v_and_b32_e32 v43, 0xffff0000, v34
	v_pk_fma_f32 v[38:39], v[12:13], v[28:29], v[38:39]
	v_pk_fma_f32 v[32:33], v[6:7], v[28:29], v[32:33] neg_lo:[0,0,1] neg_hi:[0,0,1]
	v_lshlrev_b32_e32 v28, 16, v30
	v_and_b32_e32 v29, 0xffff0000, v30
	v_pk_mul_f32 v[44:45], v[10:11], v[42:43]
	v_pk_mul_f32 v[42:43], v[16:17], v[42:43]
	v_pk_fma_f32 v[44:45], v[16:17], v[28:29], v[44:45]
	v_pk_fma_f32 v[42:43], v[10:11], v[28:29], v[42:43] neg_lo:[0,0,1] neg_hi:[0,0,1]
	v_lshlrev_b32_e32 v28, 16, v31
	v_and_b32_e32 v29, 0xffff0000, v31
	v_lshlrev_b32_e32 v30, 16, v35
	v_and_b32_e32 v31, 0xffff0000, v35
	v_pk_mul_f32 v[34:35], v[14:15], v[30:31]
	v_pk_mul_f32 v[30:31], v[24:25], v[30:31]
	v_pk_fma_f32 v[34:35], v[24:25], v[28:29], v[34:35]
	v_pk_fma_f32 v[46:47], v[14:15], v[28:29], v[30:31] neg_lo:[0,0,1] neg_hi:[0,0,1]
	v_cvt_pk_bf16_f32 v28, v36, v37
	v_cvt_pk_bf16_f32 v29, v32, v33
	v_cvt_pk_bf16_f32 v30, v42, v43
	v_cvt_pk_bf16_f32 v31, v46, v47
	global_store_dwordx4 v[4:5], v[28:31], off
	global_store_dwordx4 v[62:63], v[28:31], off
	s_nop 1
	v_cvt_pk_bf16_f32 v28, v40, v41
	v_cvt_pk_bf16_f32 v29, v38, v39
	v_cvt_pk_bf16_f32 v30, v44, v45
	v_cvt_pk_bf16_f32 v31, v34, v35
	global_store_dwordx4 v[4:5], v[28:31], off offset:64
	global_store_dwordx4 v[62:63], v[28:31], off offset:2048
	s_movk_i32 s74, 0x340
	v_lshl_add_u64 v[4:5], s[74:75], 1, v[22:23]
	s_and_b32 s98, s74, 64
	s_lshl_b32 s98, s98, 16
	v_lshl_add_u64 v[62:63], v[60:61], 0, s[98:99]
	global_load_dwordx4 v[28:31], v[4:5], off
	global_load_dwordx4 v[32:35], v[4:5], off offset:64
	s_waitcnt vmcnt(0) lgkmcnt(0)
	v_lshlrev_b32_e32 v36, 16, v28
	v_lshlrev_b32_e32 v38, 16, v32
	v_and_b32_e32 v39, 0xffff0000, v32
	v_and_b32_e32 v37, 0xffff0000, v28
	v_pk_mul_f32 v[40:41], v[2:3], v[38:39]
	v_pk_mul_f32 v[38:39], v[8:9], v[38:39]
	v_lshlrev_b32_e32 v32, 16, v33
	v_and_b32_e32 v33, 0xffff0000, v33
	v_pk_fma_f32 v[40:41], v[8:9], v[36:37], v[40:41]
	v_pk_fma_f32 v[36:37], v[2:3], v[36:37], v[38:39] neg_lo:[0,0,1] neg_hi:[0,0,1]
	v_lshlrev_b32_e32 v28, 16, v29
	v_and_b32_e32 v29, 0xffff0000, v29
	v_pk_mul_f32 v[38:39], v[6:7], v[32:33]
	v_pk_mul_f32 v[32:33], v[12:13], v[32:33]
	v_lshlrev_b32_e32 v42, 16, v34
	v_and_b32_e32 v43, 0xffff0000, v34
	v_pk_fma_f32 v[38:39], v[12:13], v[28:29], v[38:39]
	v_pk_fma_f32 v[32:33], v[6:7], v[28:29], v[32:33] neg_lo:[0,0,1] neg_hi:[0,0,1]
	v_lshlrev_b32_e32 v28, 16, v30
	v_and_b32_e32 v29, 0xffff0000, v30
	v_pk_mul_f32 v[44:45], v[10:11], v[42:43]
	v_pk_mul_f32 v[42:43], v[16:17], v[42:43]
	v_pk_fma_f32 v[44:45], v[16:17], v[28:29], v[44:45]
	v_pk_fma_f32 v[42:43], v[10:11], v[28:29], v[42:43] neg_lo:[0,0,1] neg_hi:[0,0,1]
	v_lshlrev_b32_e32 v28, 16, v31
	v_and_b32_e32 v29, 0xffff0000, v31
	v_lshlrev_b32_e32 v30, 16, v35
	v_and_b32_e32 v31, 0xffff0000, v35
	v_pk_mul_f32 v[34:35], v[14:15], v[30:31]
	v_pk_mul_f32 v[30:31], v[24:25], v[30:31]
	v_pk_fma_f32 v[34:35], v[24:25], v[28:29], v[34:35]
	v_pk_fma_f32 v[46:47], v[14:15], v[28:29], v[30:31] neg_lo:[0,0,1] neg_hi:[0,0,1]
	v_cvt_pk_bf16_f32 v28, v36, v37
	v_cvt_pk_bf16_f32 v29, v32, v33
	v_cvt_pk_bf16_f32 v30, v42, v43
	v_cvt_pk_bf16_f32 v31, v46, v47
	global_store_dwordx4 v[4:5], v[28:31], off
	global_store_dwordx4 v[62:63], v[28:31], off
	s_nop 1
	v_cvt_pk_bf16_f32 v28, v40, v41
	v_cvt_pk_bf16_f32 v29, v38, v39
	v_cvt_pk_bf16_f32 v30, v44, v45
	v_cvt_pk_bf16_f32 v31, v34, v35
	global_store_dwordx4 v[4:5], v[28:31], off offset:64
	global_store_dwordx4 v[62:63], v[28:31], off offset:2048
	s_movk_i32 s74, 0x400
	v_lshl_add_u64 v[4:5], s[74:75], 1, v[22:23]
	global_load_dwordx4 v[28:31], v[4:5], off
	global_load_dwordx4 v[32:35], v[4:5], off offset:64
	s_waitcnt vmcnt(0) lgkmcnt(0)
	v_lshlrev_b32_e32 v36, 16, v28
	v_lshlrev_b32_e32 v38, 16, v32
	v_and_b32_e32 v39, 0xffff0000, v32
	v_and_b32_e32 v37, 0xffff0000, v28
	v_pk_mul_f32 v[40:41], v[2:3], v[38:39]
	v_pk_mul_f32 v[38:39], v[8:9], v[38:39]
	v_lshlrev_b32_e32 v32, 16, v33
	v_and_b32_e32 v33, 0xffff0000, v33
	v_pk_fma_f32 v[40:41], v[8:9], v[36:37], v[40:41]
	v_pk_fma_f32 v[36:37], v[2:3], v[36:37], v[38:39] neg_lo:[0,0,1] neg_hi:[0,0,1]
	v_lshlrev_b32_e32 v28, 16, v29
	v_and_b32_e32 v29, 0xffff0000, v29
	v_pk_mul_f32 v[38:39], v[6:7], v[32:33]
	v_pk_mul_f32 v[32:33], v[12:13], v[32:33]
	v_lshlrev_b32_e32 v42, 16, v34
	v_and_b32_e32 v43, 0xffff0000, v34
	v_pk_fma_f32 v[38:39], v[12:13], v[28:29], v[38:39]
	v_pk_fma_f32 v[32:33], v[6:7], v[28:29], v[32:33] neg_lo:[0,0,1] neg_hi:[0,0,1]
	v_lshlrev_b32_e32 v28, 16, v30
	v_and_b32_e32 v29, 0xffff0000, v30
	v_pk_mul_f32 v[44:45], v[10:11], v[42:43]
	v_pk_mul_f32 v[42:43], v[16:17], v[42:43]
	v_pk_fma_f32 v[44:45], v[16:17], v[28:29], v[44:45]
	v_pk_fma_f32 v[42:43], v[10:11], v[28:29], v[42:43] neg_lo:[0,0,1] neg_hi:[0,0,1]
	v_lshlrev_b32_e32 v28, 16, v31
	v_and_b32_e32 v29, 0xffff0000, v31
	v_lshlrev_b32_e32 v30, 16, v35
	v_and_b32_e32 v31, 0xffff0000, v35
	v_pk_mul_f32 v[34:35], v[14:15], v[30:31]
	v_pk_mul_f32 v[30:31], v[24:25], v[30:31]
	v_pk_fma_f32 v[34:35], v[24:25], v[28:29], v[34:35]
	v_pk_fma_f32 v[46:47], v[14:15], v[28:29], v[30:31] neg_lo:[0,0,1] neg_hi:[0,0,1]
	v_cvt_pk_bf16_f32 v28, v36, v37
	v_cvt_pk_bf16_f32 v29, v32, v33
	v_cvt_pk_bf16_f32 v30, v42, v43
	v_cvt_pk_bf16_f32 v31, v46, v47
	global_store_dwordx4 v[4:5], v[28:31], off
	s_nop 1
	v_cvt_pk_bf16_f32 v28, v40, v41
	v_cvt_pk_bf16_f32 v29, v38, v39
	v_cvt_pk_bf16_f32 v30, v44, v45
	v_cvt_pk_bf16_f32 v31, v34, v35
	global_store_dwordx4 v[4:5], v[28:31], off offset:64
	s_movk_i32 s74, 0x440
	v_lshl_add_u64 v[4:5], s[74:75], 1, v[22:23]
	global_load_dwordx4 v[28:31], v[4:5], off
	global_load_dwordx4 v[32:35], v[4:5], off offset:64
	s_waitcnt vmcnt(0) lgkmcnt(0)
	v_lshlrev_b32_e32 v36, 16, v28
	v_lshlrev_b32_e32 v38, 16, v32
	v_and_b32_e32 v39, 0xffff0000, v32
	v_and_b32_e32 v37, 0xffff0000, v28
	v_pk_mul_f32 v[40:41], v[2:3], v[38:39]
	v_pk_mul_f32 v[38:39], v[8:9], v[38:39]
	v_lshlrev_b32_e32 v32, 16, v33
	v_and_b32_e32 v33, 0xffff0000, v33
	v_pk_fma_f32 v[40:41], v[8:9], v[36:37], v[40:41]
	v_pk_fma_f32 v[36:37], v[2:3], v[36:37], v[38:39] neg_lo:[0,0,1] neg_hi:[0,0,1]
	v_lshlrev_b32_e32 v28, 16, v29
	v_and_b32_e32 v29, 0xffff0000, v29
	v_pk_mul_f32 v[38:39], v[6:7], v[32:33]
	v_pk_mul_f32 v[32:33], v[12:13], v[32:33]
	v_lshlrev_b32_e32 v42, 16, v34
	v_and_b32_e32 v43, 0xffff0000, v34
	v_pk_fma_f32 v[38:39], v[12:13], v[28:29], v[38:39]
	v_pk_fma_f32 v[32:33], v[6:7], v[28:29], v[32:33] neg_lo:[0,0,1] neg_hi:[0,0,1]
	v_lshlrev_b32_e32 v28, 16, v30
	v_and_b32_e32 v29, 0xffff0000, v30
	v_pk_mul_f32 v[44:45], v[10:11], v[42:43]
	v_pk_mul_f32 v[42:43], v[16:17], v[42:43]
	v_pk_fma_f32 v[44:45], v[16:17], v[28:29], v[44:45]
	v_pk_fma_f32 v[42:43], v[10:11], v[28:29], v[42:43] neg_lo:[0,0,1] neg_hi:[0,0,1]
	v_lshlrev_b32_e32 v28, 16, v31
	v_and_b32_e32 v29, 0xffff0000, v31
	v_lshlrev_b32_e32 v30, 16, v35
	v_and_b32_e32 v31, 0xffff0000, v35
	v_pk_mul_f32 v[34:35], v[14:15], v[30:31]
	v_pk_mul_f32 v[30:31], v[24:25], v[30:31]
	v_pk_fma_f32 v[34:35], v[24:25], v[28:29], v[34:35]
	v_pk_fma_f32 v[46:47], v[14:15], v[28:29], v[30:31] neg_lo:[0,0,1] neg_hi:[0,0,1]
	v_cvt_pk_bf16_f32 v28, v36, v37
	v_cvt_pk_bf16_f32 v29, v32, v33
	v_cvt_pk_bf16_f32 v30, v42, v43
	v_cvt_pk_bf16_f32 v31, v46, v47
	global_store_dwordx4 v[4:5], v[28:31], off
	s_nop 1
	v_cvt_pk_bf16_f32 v28, v40, v41
	v_cvt_pk_bf16_f32 v29, v38, v39
	v_cvt_pk_bf16_f32 v30, v44, v45
	v_cvt_pk_bf16_f32 v31, v34, v35
	global_store_dwordx4 v[4:5], v[28:31], off offset:64
	s_movk_i32 s74, 0x700
	v_lshl_add_u64 v[4:5], s[74:75], 1, v[22:23]
	global_load_dwordx4 v[28:31], v[4:5], off
	global_load_dwordx4 v[32:35], v[4:5], off offset:64
	s_waitcnt vmcnt(0) lgkmcnt(0)
	v_lshlrev_b32_e32 v36, 16, v28
	v_lshlrev_b32_e32 v38, 16, v32
	v_and_b32_e32 v39, 0xffff0000, v32
	v_and_b32_e32 v37, 0xffff0000, v28
	v_pk_mul_f32 v[40:41], v[2:3], v[38:39]
	v_pk_mul_f32 v[38:39], v[8:9], v[38:39]
	v_lshlrev_b32_e32 v32, 16, v33
	v_and_b32_e32 v33, 0xffff0000, v33
	v_pk_fma_f32 v[40:41], v[8:9], v[36:37], v[40:41]
	v_pk_fma_f32 v[36:37], v[2:3], v[36:37], v[38:39] neg_lo:[0,0,1] neg_hi:[0,0,1]
	v_lshlrev_b32_e32 v28, 16, v29
	v_and_b32_e32 v29, 0xffff0000, v29
	v_pk_mul_f32 v[38:39], v[6:7], v[32:33]
	v_pk_mul_f32 v[32:33], v[12:13], v[32:33]
	v_lshlrev_b32_e32 v42, 16, v34
	v_and_b32_e32 v43, 0xffff0000, v34
	v_pk_fma_f32 v[38:39], v[12:13], v[28:29], v[38:39]
	v_pk_fma_f32 v[32:33], v[6:7], v[28:29], v[32:33] neg_lo:[0,0,1] neg_hi:[0,0,1]
	v_lshlrev_b32_e32 v28, 16, v30
	v_and_b32_e32 v29, 0xffff0000, v30
	v_pk_mul_f32 v[44:45], v[10:11], v[42:43]
	v_pk_mul_f32 v[42:43], v[16:17], v[42:43]
	v_pk_fma_f32 v[44:45], v[16:17], v[28:29], v[44:45]
	v_pk_fma_f32 v[42:43], v[10:11], v[28:29], v[42:43] neg_lo:[0,0,1] neg_hi:[0,0,1]
	v_lshlrev_b32_e32 v28, 16, v31
	v_and_b32_e32 v29, 0xffff0000, v31
	v_lshlrev_b32_e32 v30, 16, v35
	v_and_b32_e32 v31, 0xffff0000, v35
	v_pk_mul_f32 v[34:35], v[14:15], v[30:31]
	v_pk_mul_f32 v[30:31], v[24:25], v[30:31]
	v_pk_fma_f32 v[34:35], v[24:25], v[28:29], v[34:35]
	v_pk_fma_f32 v[46:47], v[14:15], v[28:29], v[30:31] neg_lo:[0,0,1] neg_hi:[0,0,1]
	v_cvt_pk_bf16_f32 v28, v36, v37
	v_cvt_pk_bf16_f32 v29, v32, v33
	v_cvt_pk_bf16_f32 v30, v42, v43
	v_cvt_pk_bf16_f32 v31, v46, v47
	global_store_dwordx4 v[4:5], v[28:31], off
	s_nop 1
	v_cvt_pk_bf16_f32 v28, v40, v41
	v_cvt_pk_bf16_f32 v29, v38, v39
	v_cvt_pk_bf16_f32 v30, v44, v45
	v_cvt_pk_bf16_f32 v31, v34, v35
	global_store_dwordx4 v[4:5], v[28:31], off offset:64
	s_branch .LBB0_332

.LBB0_442:
	s_or_b64 exec, exec, s[4:5]
	s_waitcnt vmcnt(0) lgkmcnt(0)
	v_readfirstlane_b32 s12, v0
	s_cmp_ge_u32 s12, s41
	s_mov_b64 s[4:5], -1
	s_cbranch_scc1 .LBB0_439
	s_cmp_ge_u32 s12, s40
	s_cbranch_scc0 .LBB0_462
	v_mov_b64_e32 v[2:3], s[0:1]
	global_load_dwordx2 v[2:3], v[2:3], off offset:56
	s_sub_i32 s4, s12, s40
	s_lshr_b32 s5, s4, 9
	s_lshl_b32 s4, s4, 3
	v_mov_b32_e32 v151, v194
	s_and_b32 s13, s4, 0xff8
	s_mul_i32 s5, s5, s36
	v_bfe_u32 v0, v151, 3, 2
	v_cmp_gt_u32_e32 vcc, 32, v151
	v_or_b32_e32 v174, s13, v0
	v_mov_b32_e32 v0, 0x7f
	s_add_i32 s8, s5, s80
	v_cndmask_b32_e64 v170, 0, 1.0, vcc
	v_sub_co_u32_e32 v0, vcc, s13, v0
	s_ashr_i32 s9, s8, 31
	v_readfirstlane_b32 s4, v0
	s_lshl_b64 s[6:7], s[8:9], 12
	s_and_b32 s10, s4, 0xffffffe0
	s_and_b64 s[4:5], vcc, exec
	v_ashrrev_i32_e32 v4, 5, v151
	v_or_b32_e32 v175, 4, v174
	s_cselect_b32 s10, 0, s10
	s_or_b32 s14, s13, 7
	s_mov_b64 s[4:5], -1
	s_cmp_le_i32 s10, s14
	v_or_b32_e32 v146, s6, v175
	v_or_b32_e32 v148, s6, v174
	v_lshlrev_b32_e32 v172, 2, v4
	s_cbranch_scc0 .LBB0_459
	v_and_b32_e32 v5, 31, v151
	v_mov_b32_e32 v0, 0x1400000
	v_lshlrev_b32_e32 v6, 3, v4
	v_mad_i64_i32 v[8:9], s[4:5], s8, v0, v[154:155]
	v_mul_u32_u24_e32 v0, 0xa00, v5
	v_ashrrev_i32_e32 v7, 31, v6
	v_lshlrev_b32_e32 v0, 1, v0
	v_readlane_b32 s4, v255, 15
	v_lshl_add_u64 v[8:9], v[8:9], 0, v[0:1]
	v_lshlrev_b64 v[6:7], 1, v[6:7]
	v_readlane_b32 s5, v255, 16
	v_lshl_add_u64 v[152:153], v[8:9], 0, v[6:7]
	v_and_b32_e32 v10, 7, v151
	s_waitcnt vmcnt(0) lgkmcnt(0)
	v_lshl_add_u64 v[2:3], v[2:3], 0, s[4:5]
	v_mad_u64_u32 v[8:9], s[4:5], v146, s61, v[154:155]
	v_mad_i32_i24 v9, s7, v247, v9
	v_lshlrev_b32_e32 v0, 7, v10
	v_lshl_add_u64 v[8:9], v[8:9], 0, v[0:1]
	v_lshl_add_u64 v[8:9], v[8:9], 0, v[6:7]
	global_load_dwordx4 v[82:85], v[8:9], off offset:2656
	global_load_dwordx4 v[86:89], v[8:9], off offset:2624
	global_load_dwordx4 v[90:93], v[8:9], off offset:2592
	global_load_dwordx4 v[94:97], v[8:9], off offset:2560
	v_mad_u64_u32 v[8:9], s[4:5], v148, s61, v[154:155]
	v_mad_i32_i24 v9, s7, v247, v9
	v_lshl_add_u64 v[8:9], v[8:9], 0, v[0:1]
	v_lshlrev_b32_e32 v0, 2, v10
	v_lshl_add_u64 v[8:9], v[8:9], 0, v[6:7]
	v_lshl_add_u64 v[2:3], v[2:3], 0, v[0:1]
	global_load_dwordx4 v[98:101], v[8:9], off offset:2656
	global_load_dwordx4 v[102:105], v[8:9], off offset:2624
	global_load_dwordx4 v[106:109], v[8:9], off offset:2592
	global_load_dwordx4 v[110:113], v[8:9], off offset:2560
	s_mov_b32 s100, 0xf9800000
	s_mov_b32 s101, -1
	v_lshlrev_b32_e32 v140, 8, v146
	v_lshl_add_u32 v140, v6, 2, v140
	v_mov_b32_e32 v141, 0
	v_lshl_add_u64 v[140:141], v[154:155], 0, v[140:141]
	v_lshl_add_u64 v[140:141], v[140:141], 0, s[100:101]
	global_load_dwordx4 v[16:19], v[140:141], off offset:0
	global_load_dwordx4 v[20:23], v[140:141], off offset:16
	global_load_dwordx4 v[24:27], v[140:141], off offset:32
	global_load_dwordx4 v[28:31], v[140:141], off offset:48
	global_load_dwordx4 v[32:35], v[140:141], off offset:128
	global_load_dwordx4 v[36:39], v[140:141], off offset:144
	global_load_dwordx4 v[40:43], v[140:141], off offset:160
	global_load_dwordx4 v[44:47], v[140:141], off offset:176
	v_lshlrev_b32_e32 v140, 8, v148
	v_lshl_add_u32 v140, v6, 2, v140
	v_mov_b32_e32 v141, 0
	v_lshl_add_u64 v[140:141], v[154:155], 0, v[140:141]
	v_lshl_add_u64 v[140:141], v[140:141], 0, s[100:101]
	global_load_dwordx4 v[48:51], v[140:141], off offset:0
	global_load_dwordx4 v[52:55], v[140:141], off offset:16
	global_load_dwordx4 v[56:59], v[140:141], off offset:32
	global_load_dwordx4 v[60:63], v[140:141], off offset:48
	global_load_dwordx4 v[66:69], v[140:141], off offset:128
	global_load_dwordx4 v[70:73], v[140:141], off offset:144
	global_load_dwordx4 v[74:77], v[140:141], off offset:160
	global_load_dwordx4 v[78:81], v[140:141], off offset:176
	global_load_dword v0, v[2:3], off
	s_mul_i32 s4, s10, 0xa00
	s_ashr_i32 s5, s4, 31
	v_lshl_add_u64 v[2:3], s[4:5], 1, v[152:153]
	global_load_dwordx4 v[114:117], v[2:3], off offset:3680
	global_load_dwordx4 v[118:121], v[2:3], off offset:3648
	global_load_dwordx4 v[122:125], v[2:3], off offset:3616
	global_load_dwordx4 v[126:129], v[2:3], off offset:3584
	s_ashr_i32 s11, s10, 31
	s_lshl_b64 s[4:5], s[8:9], 19
	s_lshl_b64 s[8:9], s[10:11], 7
	s_add_u32 s4, s4, s8
	s_addc_u32 s5, s5, s9
	s_add_i32 s6, s13, 0xffffff87
	s_add_u32 s4, s4, 0x1000000
	s_addc_u32 s5, s5, 0
	v_mov_b32_e32 v14, v1
	v_mov_b32_e32 v15, v1
	v_lshlrev_b32_e32 v150, 2, v4
	v_mov_b32_e32 v4, v1
	v_mov_b32_e32 v8, v1
	v_mov_b32_e32 v9, v1
	v_mov_b32_e32 v10, v1
	v_mov_b32_e32 v11, v1
	v_mov_b32_e32 v12, v1
	v_mov_b32_e32 v13, v1
	v_mov_b32_e32 v147, s7
	v_mov_b32_e32 v149, s7
	v_add_u32_e32 v176, 0xffffff80, v174
	v_add_u32_e32 v177, 0xffffff84, v174
	v_mov_b32_e32 v171, v170
	v_mov_b32_e32 v173, v170
	s_waitcnt vmcnt(0) lgkmcnt(0)
	v_lshlrev_b32_e32 v130, 16, v94
	v_and_b32_e32 v131, 0xffff0000, v94
	v_lshlrev_b32_e32 v132, 16, v86
	v_and_b32_e32 v133, 0xffff0000, v86
	v_mul_f32_e32 v134, v17, v132
	v_mul_f32_e32 v135, v19, v133
	v_mul_f32_e32 v136, v16, v132
	v_mul_f32_e32 v137, v18, v133
	v_fma_f32 v134, v16, v130, -v134
	v_fma_f32 v135, v18, v131, -v135
	v_fma_f32 v136, v17, v130, v136
	v_fma_f32 v137, v19, v131, v137
	v_cvt_pk_bf16_f32 v94, v134, v135
	v_cvt_pk_bf16_f32 v86, v136, v137
	v_lshlrev_b32_e32 v130, 16, v95
	v_and_b32_e32 v131, 0xffff0000, v95
	v_lshlrev_b32_e32 v132, 16, v87
	v_and_b32_e32 v133, 0xffff0000, v87
	v_mul_f32_e32 v134, v21, v132
	v_mul_f32_e32 v135, v23, v133
	v_mul_f32_e32 v136, v20, v132
	v_mul_f32_e32 v137, v22, v133
	v_fma_f32 v134, v20, v130, -v134
	v_fma_f32 v135, v22, v131, -v135
	v_fma_f32 v136, v21, v130, v136
	v_fma_f32 v137, v23, v131, v137
	v_cvt_pk_bf16_f32 v95, v134, v135
	v_cvt_pk_bf16_f32 v87, v136, v137
	v_lshlrev_b32_e32 v130, 16, v96
	v_and_b32_e32 v131, 0xffff0000, v96
	v_lshlrev_b32_e32 v132, 16, v88
	v_and_b32_e32 v133, 0xffff0000, v88
	v_mul_f32_e32 v134, v25, v132
	v_mul_f32_e32 v135, v27, v133
	v_mul_f32_e32 v136, v24, v132
	v_mul_f32_e32 v137, v26, v133
	v_fma_f32 v134, v24, v130, -v134
	v_fma_f32 v135, v26, v131, -v135
	v_fma_f32 v136, v25, v130, v136
	v_fma_f32 v137, v27, v131, v137
	v_cvt_pk_bf16_f32 v96, v134, v135
	v_cvt_pk_bf16_f32 v88, v136, v137
	v_lshlrev_b32_e32 v130, 16, v97
	v_and_b32_e32 v131, 0xffff0000, v97
	v_lshlrev_b32_e32 v132, 16, v89
	v_and_b32_e32 v133, 0xffff0000, v89
	v_mul_f32_e32 v134, v29, v132
	v_mul_f32_e32 v135, v31, v133
	v_mul_f32_e32 v136, v28, v132
	v_mul_f32_e32 v137, v30, v133
	v_fma_f32 v134, v28, v130, -v134
	v_fma_f32 v135, v30, v131, -v135
	v_fma_f32 v136, v29, v130, v136
	v_fma_f32 v137, v31, v131, v137
	v_cvt_pk_bf16_f32 v97, v134, v135
	v_cvt_pk_bf16_f32 v89, v136, v137
	v_lshlrev_b32_e32 v130, 16, v90
	v_and_b32_e32 v131, 0xffff0000, v90
	v_lshlrev_b32_e32 v132, 16, v82
	v_and_b32_e32 v133, 0xffff0000, v82
	v_mul_f32_e32 v134, v33, v132
	v_mul_f32_e32 v135, v35, v133
	v_mul_f32_e32 v136, v32, v132
	v_mul_f32_e32 v137, v34, v133
	v_fma_f32 v134, v32, v130, -v134
	v_fma_f32 v135, v34, v131, -v135
	v_fma_f32 v136, v33, v130, v136
	v_fma_f32 v137, v35, v131, v137
	v_cvt_pk_bf16_f32 v90, v134, v135
	v_cvt_pk_bf16_f32 v82, v136, v137
	v_lshlrev_b32_e32 v130, 16, v91
	v_and_b32_e32 v131, 0xffff0000, v91
	v_lshlrev_b32_e32 v132, 16, v83
	v_and_b32_e32 v133, 0xffff0000, v83
	v_mul_f32_e32 v134, v37, v132
	v_mul_f32_e32 v135, v39, v133
	v_mul_f32_e32 v136, v36, v132
	v_mul_f32_e32 v137, v38, v133
	v_fma_f32 v134, v36, v130, -v134
	v_fma_f32 v135, v38, v131, -v135
	v_fma_f32 v136, v37, v130, v136
	v_fma_f32 v137, v39, v131, v137
	v_cvt_pk_bf16_f32 v91, v134, v135
	v_cvt_pk_bf16_f32 v83, v136, v137
	v_lshlrev_b32_e32 v130, 16, v92
	v_and_b32_e32 v131, 0xffff0000, v92
	v_lshlrev_b32_e32 v132, 16, v84
	v_and_b32_e32 v133, 0xffff0000, v84
	v_mul_f32_e32 v134, v41, v132
	v_mul_f32_e32 v135, v43, v133
	v_mul_f32_e32 v136, v40, v132
	v_mul_f32_e32 v137, v42, v133
	v_fma_f32 v134, v40, v130, -v134
	v_fma_f32 v135, v42, v131, -v135
	v_fma_f32 v136, v41, v130, v136
	v_fma_f32 v137, v43, v131, v137
	v_cvt_pk_bf16_f32 v92, v134, v135
	v_cvt_pk_bf16_f32 v84, v136, v137
	v_lshlrev_b32_e32 v130, 16, v93
	v_and_b32_e32 v131, 0xffff0000, v93
	v_lshlrev_b32_e32 v132, 16, v85
	v_and_b32_e32 v133, 0xffff0000, v85
	v_mul_f32_e32 v134, v45, v132
	v_mul_f32_e32 v135, v47, v133
	v_mul_f32_e32 v136, v44, v132
	v_mul_f32_e32 v137, v46, v133
	v_fma_f32 v134, v44, v130, -v134
	v_fma_f32 v135, v46, v131, -v135
	v_fma_f32 v136, v45, v130, v136
	v_fma_f32 v137, v47, v131, v137
	v_cvt_pk_bf16_f32 v93, v134, v135
	v_cvt_pk_bf16_f32 v85, v136, v137
	v_lshlrev_b32_e32 v130, 16, v110
	v_and_b32_e32 v131, 0xffff0000, v110
	v_lshlrev_b32_e32 v132, 16, v102
	v_and_b32_e32 v133, 0xffff0000, v102
	v_mul_f32_e32 v134, v49, v132
	v_mul_f32_e32 v135, v51, v133
	v_mul_f32_e32 v136, v48, v132
	v_mul_f32_e32 v137, v50, v133
	v_fma_f32 v134, v48, v130, -v134
	v_fma_f32 v135, v50, v131, -v135
	v_fma_f32 v136, v49, v130, v136
	v_fma_f32 v137, v51, v131, v137
	v_cvt_pk_bf16_f32 v110, v134, v135
	v_cvt_pk_bf16_f32 v102, v136, v137
	v_lshlrev_b32_e32 v130, 16, v111
	v_and_b32_e32 v131, 0xffff0000, v111
	v_lshlrev_b32_e32 v132, 16, v103
	v_and_b32_e32 v133, 0xffff0000, v103
	v_mul_f32_e32 v134, v53, v132
	v_mul_f32_e32 v135, v55, v133
	v_mul_f32_e32 v136, v52, v132
	v_mul_f32_e32 v137, v54, v133
	v_fma_f32 v134, v52, v130, -v134
	v_fma_f32 v135, v54, v131, -v135
	v_fma_f32 v136, v53, v130, v136
	v_fma_f32 v137, v55, v131, v137
	v_cvt_pk_bf16_f32 v111, v134, v135
	v_cvt_pk_bf16_f32 v103, v136, v137
	v_lshlrev_b32_e32 v130, 16, v112
	v_and_b32_e32 v131, 0xffff0000, v112
	v_lshlrev_b32_e32 v132, 16, v104
	v_and_b32_e32 v133, 0xffff0000, v104
	v_mul_f32_e32 v134, v57, v132
	v_mul_f32_e32 v135, v59, v133
	v_mul_f32_e32 v136, v56, v132
	v_mul_f32_e32 v137, v58, v133
	v_fma_f32 v134, v56, v130, -v134
	v_fma_f32 v135, v58, v131, -v135
	v_fma_f32 v136, v57, v130, v136
	v_fma_f32 v137, v59, v131, v137
	v_cvt_pk_bf16_f32 v112, v134, v135
	v_cvt_pk_bf16_f32 v104, v136, v137
	v_lshlrev_b32_e32 v130, 16, v113
	v_and_b32_e32 v131, 0xffff0000, v113
	v_lshlrev_b32_e32 v132, 16, v105
	v_and_b32_e32 v133, 0xffff0000, v105
	v_mul_f32_e32 v134, v61, v132
	v_mul_f32_e32 v135, v63, v133
	v_mul_f32_e32 v136, v60, v132
	v_mul_f32_e32 v137, v62, v133
	v_fma_f32 v134, v60, v130, -v134
	v_fma_f32 v135, v62, v131, -v135
	v_fma_f32 v136, v61, v130, v136
	v_fma_f32 v137, v63, v131, v137
	v_cvt_pk_bf16_f32 v113, v134, v135
	v_cvt_pk_bf16_f32 v105, v136, v137
	v_lshlrev_b32_e32 v130, 16, v106
	v_and_b32_e32 v131, 0xffff0000, v106
	v_lshlrev_b32_e32 v132, 16, v98
	v_and_b32_e32 v133, 0xffff0000, v98
	v_mul_f32_e32 v134, v67, v132
	v_mul_f32_e32 v135, v69, v133
	v_mul_f32_e32 v136, v66, v132
	v_mul_f32_e32 v137, v68, v133
	v_fma_f32 v134, v66, v130, -v134
	v_fma_f32 v135, v68, v131, -v135
	v_fma_f32 v136, v67, v130, v136
	v_fma_f32 v137, v69, v131, v137
	v_cvt_pk_bf16_f32 v106, v134, v135
	v_cvt_pk_bf16_f32 v98, v136, v137
	v_lshlrev_b32_e32 v130, 16, v107
	v_and_b32_e32 v131, 0xffff0000, v107
	v_lshlrev_b32_e32 v132, 16, v99
	v_and_b32_e32 v133, 0xffff0000, v99
	v_mul_f32_e32 v134, v71, v132
	v_mul_f32_e32 v135, v73, v133
	v_mul_f32_e32 v136, v70, v132
	v_mul_f32_e32 v137, v72, v133
	v_fma_f32 v134, v70, v130, -v134
	v_fma_f32 v135, v72, v131, -v135
	v_fma_f32 v136, v71, v130, v136
	v_fma_f32 v137, v73, v131, v137
	v_cvt_pk_bf16_f32 v107, v134, v135
	v_cvt_pk_bf16_f32 v99, v136, v137
	v_lshlrev_b32_e32 v130, 16, v108
	v_and_b32_e32 v131, 0xffff0000, v108
	v_lshlrev_b32_e32 v132, 16, v100
	v_and_b32_e32 v133, 0xffff0000, v100
	v_mul_f32_e32 v134, v75, v132
	v_mul_f32_e32 v135, v77, v133
	v_mul_f32_e32 v136, v74, v132
	v_mul_f32_e32 v137, v76, v133
	v_fma_f32 v134, v74, v130, -v134
	v_fma_f32 v135, v76, v131, -v135
	v_fma_f32 v136, v75, v130, v136
	v_fma_f32 v137, v77, v131, v137
	v_cvt_pk_bf16_f32 v108, v134, v135
	v_cvt_pk_bf16_f32 v100, v136, v137
	v_lshlrev_b32_e32 v130, 16, v109
	v_and_b32_e32 v131, 0xffff0000, v109
	v_lshlrev_b32_e32 v132, 16, v101
	v_and_b32_e32 v133, 0xffff0000, v101
	v_mul_f32_e32 v134, v79, v132
	v_mul_f32_e32 v135, v81, v133
	v_mul_f32_e32 v136, v78, v132
	v_mul_f32_e32 v137, v80, v133
	v_fma_f32 v134, v78, v130, -v134
	v_fma_f32 v135, v80, v131, -v135
	v_fma_f32 v136, v79, v130, v136
	v_fma_f32 v137, v81, v131, v137
	v_cvt_pk_bf16_f32 v109, v134, v135
	v_cvt_pk_bf16_f32 v101, v136, v137
	v_mul_f32_e32 v178, 0x3fb8aa3b, v0
	v_lshlrev_b32_e32 v0, 5, v5
	v_lshl_add_u64 v[2:3], s[4:5], 0, v[0:1]
	v_lshl_add_u64 v[2:3], v[2:3], 0, v[6:7]
	v_lshl_add_u64 v[168:169], v[164:165], 0, v[2:3]
	v_mov_b32_e32 v0, v1
	v_mov_b32_e32 v2, v1
	v_mov_b32_e32 v3, v1
	v_mov_b32_e32 v5, v1
	v_mov_b32_e32 v6, v1
	v_mov_b32_e32 v7, v1
	v_mov_b64_e32 v[64:65], v[14:15]
	v_mov_b64_e32 v[48:49], v[14:15]
	v_mov_b64_e32 v[32:33], v[14:15]
	v_mov_b64_e32 v[62:63], v[12:13]
	v_mov_b64_e32 v[60:61], v[10:11]
	v_mov_b64_e32 v[58:59], v[8:9]
	v_mov_b64_e32 v[56:57], v[6:7]
	v_mov_b64_e32 v[54:55], v[4:5]
	v_mov_b64_e32 v[52:53], v[2:3]
	v_mov_b64_e32 v[50:51], v[0:1]
	v_mov_b64_e32 v[46:47], v[12:13]
	v_mov_b64_e32 v[44:45], v[10:11]
	v_mov_b64_e32 v[42:43], v[8:9]
	v_mov_b64_e32 v[40:41], v[6:7]
	v_mov_b64_e32 v[38:39], v[4:5]
	v_mov_b64_e32 v[36:37], v[2:3]
	v_mov_b64_e32 v[34:35], v[0:1]
	v_mov_b64_e32 v[30:31], v[12:13]
	v_mov_b64_e32 v[28:29], v[10:11]
	v_mov_b64_e32 v[26:27], v[8:9]
	v_mov_b64_e32 v[24:25], v[6:7]
	v_mov_b64_e32 v[22:23], v[4:5]
	v_mov_b64_e32 v[20:21], v[2:3]
	v_mov_b64_e32 v[18:19], v[0:1]
	v_mov_b64_e32 v[16:17], v[14:15]
	v_mov_b64_e32 v[14:15], v[12:13]
	v_mov_b64_e32 v[12:13], v[10:11]
	v_mov_b64_e32 v[10:11], v[8:9]
	v_mov_b64_e32 v[8:9], v[6:7]
	v_mov_b64_e32 v[6:7], v[4:5]
	v_mov_b64_e32 v[4:5], v[2:3]
	v_mov_b64_e32 v[2:3], v[0:1]
	v_mov_b32_e32 v195, v178
